# ml3: n_in row load hoisted to the conv-window load group (was issued after the conv and waited at once) + DPP decay scan; end of text padded
# speedup vs baseline: 1.0027x; 1.0027x over previous
.LBB0_658:
	s_or_b64 exec, exec, s[0:1]
	s_lshl_b32 s0, s93, 11
	s_add_i32 s94, s0, 0
	s_lshl_b32 s0, s93, 5
	s_add_i32 s0, s0, s40
	s_or_b32 s0, s0, s38
	s_add_i32 s94, s94, 0x20000
	s_lshl_b32 s4, s0, 4
	s_and_b64 s[0:1], s[14:15], exec
	s_cselect_b32 s0, s33, s39
	v_add_u32_e32 v48, s60, v176
	v_mov_b64_e32 v[46:47], s[28:29]
	s_or_b32 s38, s4, s0
	v_mad_i64_i32 v[34:35], s[0:1], v48, s36, v[46:47]
	v_or_b32_e32 v38, 1, v48
	v_or_b32_e32 v42, 2, v48
	v_or_b32_e32 v48, 3, v48
	v_mad_i64_i32 v[38:39], s[0:1], v38, s36, v[46:47]
	v_mad_i64_i32 v[42:43], s[0:1], v42, s36, v[46:47]
	v_mad_i64_i32 v[46:47], s[0:1], v48, s36, v[46:47]
	v_lshlrev_b32_e32 v164, 2, v114
	v_mov_b32_e32 v165, v179
	v_lshl_add_u64 v[156:157], s[34:35], 0, v[164:165]
	s_mov_b64 s[0:1], 0x1000
	v_lshl_add_u64 v[118:119], v[156:157], 0, s[0:1]
	s_movk_i32 s0, 0x1000
	v_add_co_u32_e32 v166, vcc, s0, v156
	s_movk_i32 s0, 0x2000
	s_nop 0
	v_addc_co_u32_e32 v167, vcc, 0, v157, vcc
	s_lshl_b32 s82, s41, 1
	v_add_co_u32_e32 v158, vcc, s0, v156
	s_mov_b64 s[0:1], 0x2000
	v_lshl_add_u64 v[34:35], v[34:35], 0, s[82:83]
	v_lshl_add_u64 v[38:39], v[38:39], 0, s[82:83]
	v_lshl_add_u64 v[42:43], v[42:43], 0, s[82:83]
	v_lshl_add_u64 v[46:47], v[46:47], 0, s[82:83]
	v_lshl_add_u64 v[122:123], v[156:157], 0, s[0:1]
	s_mov_b64 s[0:1], 0x3000
	v_lshl_add_u64 v[34:35], v[34:35], 0, v[178:179]
	v_lshl_add_u64 v[38:39], v[38:39], 0, v[178:179]
	v_lshl_add_u64 v[42:43], v[42:43], 0, v[178:179]
	v_lshl_add_u64 v[46:47], v[46:47], 0, v[178:179]
	v_addc_co_u32_e32 v159, vcc, 0, v157, vcc
	v_lshl_add_u64 v[126:127], v[156:157], 0, s[0:1]
	s_movk_i32 s0, 0x3000
	global_load_dwordx4 v[34:37], v[34:35], off offset:2048
	v_add_co_u32_e32 v162, vcc, s0, v156
	global_load_dwordx4 v[38:41], v[38:39], off offset:2048
	s_nop 0
	v_addc_co_u32_e32 v163, vcc, 0, v157, vcc
	global_load_dwordx4 v[42:45], v[42:43], off offset:2048
	s_movk_i32 s0, 0x4000
	global_load_dwordx4 v[46:49], v[46:47], off offset:2048
	s_nop 0
	global_load_dwordx4 v[114:117], v164, s[34:35] offset:16
	global_load_dwordx4 v[134:137], v164, s[34:35]
	global_load_dwordx4 v[138:141], v[158:159], off offset:-4096
	s_nop 0
	global_load_dwordx4 v[118:121], v[118:119], off offset:16
	v_add_co_u32_e32 v160, vcc, s0, v156
	global_load_dwordx4 v[142:145], v[158:159], off
	s_nop 0
	global_load_dwordx4 v[122:125], v[122:123], off offset:16
	v_addc_co_u32_e32 v161, vcc, 0, v157, vcc
	s_mov_b64 s[0:1], 0x4000
	global_load_dwordx4 v[146:149], v[160:161], off offset:-4096
	s_nop 0
	global_load_dwordx4 v[126:129], v[126:127], off offset:16
	v_lshl_add_u64 v[130:131], v[156:157], 0, s[0:1]
	global_load_dwordx4 v[150:153], v[160:161], off
	s_nop 0
	global_load_dwordx4 v[130:133], v[130:131], off offset:16
	s_cmp_lg_u32 s61, 1
	s_cbranch_scc1 .Lml3_nonni
	s_lshl_b32 s0, s38, 9
	s_add_u32 s0, s16, s0
	s_addc_u32 s1, s17, 0
	v_lshlrev_b32_e32 v228, 2, v171
	global_load_dword v226, v228, s[0:1]
	global_load_dword v227, v228, s[0:1] offset:256
.Lml3_nonni:
	s_waitcnt vmcnt(14)
	v_lshlrev_b32_e32 v224, 16, v82
	v_and_b32_e32 v225, 0xffff0000, v82
	v_lshlrev_b32_e32 v220, 16, v86
	v_and_b32_e32 v221, 0xffff0000, v86
	v_lshlrev_b32_e32 v216, 16, v90
	v_and_b32_e32 v217, 0xffff0000, v90
	v_lshlrev_b32_e32 v196, 16, v102
	v_and_b32_e32 v197, 0xffff0000, v102
	v_lshlrev_b32_e32 v198, 16, v98
	v_and_b32_e32 v199, 0xffff0000, v98
	v_lshlrev_b32_e32 v214, 16, v106
	v_and_b32_e32 v215, 0xffff0000, v106
	v_lshlrev_b32_e32 v212, 16, v110
	v_and_b32_e32 v213, 0xffff0000, v110
	s_add_i32 s92, 0, 0x10000
	s_waitcnt vmcnt(8)
	v_pk_fma_f32 v[224:225], v[134:135], v[224:225], 0 op_sel_hi:[1,1,0]
	v_pk_fma_f32 v[222:223], v[134:135], v[220:221], 0 op_sel_hi:[1,1,0]
	s_waitcnt vmcnt(7)
	v_pk_fma_f32 v[220:221], v[138:139], v[220:221], v[224:225]
	v_pk_fma_f32 v[218:219], v[134:135], v[216:217], 0 op_sel_hi:[1,1,0]
	v_pk_fma_f32 v[222:223], v[138:139], v[216:217], v[222:223]
	s_waitcnt vmcnt(5)
	v_pk_fma_f32 v[216:217], v[142:143], v[216:217], v[220:221]
	v_pk_fma_f32 v[134:135], v[134:135], v[196:197], 0 op_sel_hi:[1,1,0]
	s_waitcnt vmcnt(3)
	v_pk_fma_f32 v[216:217], v[146:147], v[196:197], v[216:217]
	v_pk_fma_f32 v[134:135], v[138:139], v[198:199], v[134:135]
	s_waitcnt vmcnt(1)
	v_pk_fma_f32 v[216:217], v[150:151], v[198:199], v[216:217]
	v_pk_fma_f32 v[134:135], v[142:143], v[212:213], v[134:135]
	v_mul_f32_e32 v82, 0xbfb8aa3b, v216
	v_exp_f32_e32 v220, v82
	v_mul_f32_e32 v82, 0xbfb8aa3b, v217
	v_exp_f32_e32 v221, v82
	v_pk_fma_f32 v[134:135], v[146:147], v[214:215], v[134:135]
	v_pk_add_f32 v[220:221], v[220:221], 1.0 op_sel_hi:[1,0]
	s_nop 0
	v_rcp_f32_e32 v86, v221
	s_nop 0
	s_nop 0
	v_mul_f32_e32 v98, v217, v86
	v_fma_f32 v102, -v221, v98, v217
	v_fma_f32 v82, v102, v86, v98
	v_rcp_f32_e32 v90, v220
	v_div_fixup_f32 v82, v82, v221, v217
	s_nop 0
	v_mul_f32_e32 v102, v216, v90
	v_fma_f32 v106, -v220, v102, v216
	v_fma_f32 v86, v106, v90, v102
	v_div_fixup_f32 v86, v86, v220, v216
	v_pk_fma_f32 v[216:217], v[142:143], v[196:197], v[222:223]
	v_cvt_pk_bf16_f32 v82, v86, v82
	v_pk_fma_f32 v[216:217], v[146:147], v[198:199], v[216:217]
	s_nop 0
	v_pk_fma_f32 v[216:217], v[150:151], v[212:213], v[216:217]
	s_nop 0
	v_mul_f32_e32 v86, 0xbfb8aa3b, v216
	v_exp_f32_e32 v220, v86
	v_mul_f32_e32 v86, 0xbfb8aa3b, v217
	v_exp_f32_e32 v221, v86
	s_nop 0
	v_pk_add_f32 v[220:221], v[220:221], 1.0 op_sel_hi:[1,0]
	s_nop 0
	v_rcp_f32_e32 v90, v221
	s_nop 0
	s_nop 0
	v_mul_f32_e32 v102, v217, v90
	v_fma_f32 v106, -v221, v102, v217
	v_fma_f32 v86, v106, v90, v102
	v_rcp_f32_e32 v98, v220
	v_div_fixup_f32 v86, v86, v221, v217
	s_nop 0
	v_mul_f32_e32 v106, v216, v98
	v_fma_f32 v110, -v220, v106, v216
	v_fma_f32 v90, v110, v98, v106
	v_div_fixup_f32 v90, v90, v220, v216
	v_pk_fma_f32 v[216:217], v[138:139], v[196:197], v[218:219]
	v_cvt_pk_bf16_f32 v86, v90, v86
	v_pk_fma_f32 v[216:217], v[142:143], v[198:199], v[216:217]
	v_lshlrev_b32_e32 v138, 16, v94
	v_pk_fma_f32 v[216:217], v[146:147], v[212:213], v[216:217]
	v_and_b32_e32 v139, 0xffff0000, v94
	v_pk_fma_f32 v[216:217], v[150:151], v[214:215], v[216:217]
	v_pk_fma_f32 v[134:135], v[150:151], v[138:139], v[134:135]
	v_mul_f32_e32 v90, 0xbfb8aa3b, v216
	v_exp_f32_e32 v218, v90
	v_mul_f32_e32 v90, 0xbfb8aa3b, v217
	v_exp_f32_e32 v219, v90
	v_mul_f32_e32 v94, 0xbfb8aa3b, v134
	v_exp_f32_e32 v138, v94
	v_mul_f32_e32 v94, 0xbfb8aa3b, v135
	v_pk_add_f32 v[218:219], v[218:219], 1.0 op_sel_hi:[1,0]
	v_exp_f32_e32 v139, v94
	v_rcp_f32_e32 v98, v219
	v_pk_add_f32 v[138:139], v[138:139], 1.0 op_sel_hi:[1,0]
	v_lshlrev_b32_e32 v150, 16, v83
	s_nop 0
	v_mul_f32_e32 v106, v217, v98
	v_fma_f32 v110, -v219, v106, v217
	v_fma_f32 v90, v110, v98, v106
	v_rcp_f32_e32 v102, v218
	v_div_fixup_f32 v90, v90, v219, v217
	v_and_b32_e32 v151, 0xffff0000, v83
	v_lshlrev_b32_e32 v142, 16, v87
	s_nop 0
	v_mul_f32_e32 v110, v216, v102
	v_fma_f32 v155, -v218, v110, v216
	v_fma_f32 v98, v155, v102, v110
	v_div_fixup_f32 v98, v98, v218, v216
	v_cvt_pk_bf16_f32 v90, v98, v90
	v_rcp_f32_e32 v98, v139
	v_and_b32_e32 v143, 0xffff0000, v87
	v_pk_fma_f32 v[150:151], v[136:137], v[150:151], 0 op_sel_hi:[1,1,0]
	v_pk_fma_f32 v[146:147], v[136:137], v[142:143], 0 op_sel_hi:[1,1,0]
	s_nop 0
	v_mul_f32_e32 v106, v135, v98
	v_fma_f32 v110, -v139, v106, v135
	v_fma_f32 v94, v110, v98, v106
	v_div_fixup_f32 v155, v94, v139, v135
	v_rcp_f32_e32 v98, v138
	v_and_b32_e32 v135, 0xffff0000, v91
	v_pk_fma_f32 v[142:143], v[140:141], v[142:143], v[150:151]
	s_nop 0
	v_mul_f32_e32 v106, v134, v98
	v_fma_f32 v110, -v138, v106, v134
	v_fma_f32 v94, v110, v98, v106
	v_div_fixup_f32 v165, v94, v138, v134
	v_lshlrev_b32_e32 v134, 16, v91
	v_lshlrev_b32_e32 v102, 16, v103
	v_and_b32_e32 v103, 0xffff0000, v103
	v_pk_fma_f32 v[138:139], v[136:137], v[134:135], 0 op_sel_hi:[1,1,0]
	v_pk_fma_f32 v[146:147], v[140:141], v[134:135], v[146:147]
	v_pk_fma_f32 v[134:135], v[144:145], v[134:135], v[142:143]
	v_lshlrev_b32_e32 v98, 16, v99
	v_and_b32_e32 v99, 0xffff0000, v99
	v_pk_fma_f32 v[134:135], v[148:149], v[102:103], v[134:135]
	v_lshlrev_b32_e32 v110, 16, v111
	v_pk_fma_f32 v[134:135], v[152:153], v[98:99], v[134:135]
	v_and_b32_e32 v111, 0xffff0000, v111
	v_mul_f32_e32 v83, 0xbfb8aa3b, v134
	v_exp_f32_e32 v142, v83
	v_mul_f32_e32 v83, 0xbfb8aa3b, v135
	v_exp_f32_e32 v143, v83
	v_lshlrev_b32_e32 v106, 16, v107
	v_and_b32_e32 v107, 0xffff0000, v107
	v_pk_add_f32 v[142:143], v[142:143], 1.0 op_sel_hi:[1,0]
	s_nop 0
	v_rcp_f32_e32 v87, v143
	s_nop 0
	s_nop 0
	v_mul_f32_e32 v94, v135, v87
	v_fma_f32 v150, -v143, v94, v135
	v_fma_f32 v83, v150, v87, v94
	v_rcp_f32_e32 v91, v142
	v_div_fixup_f32 v83, v83, v143, v135
	s_nop 0
	v_mul_f32_e32 v135, v134, v91
	v_fma_f32 v143, -v142, v135, v134
	v_fma_f32 v87, v143, v91, v135
	v_div_fixup_f32 v87, v87, v142, v134
	v_pk_fma_f32 v[134:135], v[144:145], v[102:103], v[146:147]
	v_cvt_pk_bf16_f32 v83, v87, v83
	v_pk_fma_f32 v[134:135], v[148:149], v[98:99], v[134:135]
	s_nop 0
	v_pk_fma_f32 v[134:135], v[152:153], v[110:111], v[134:135]
	s_nop 0
	v_mul_f32_e32 v87, 0xbfb8aa3b, v134
	v_exp_f32_e32 v142, v87
	v_mul_f32_e32 v87, 0xbfb8aa3b, v135
	v_exp_f32_e32 v143, v87
	s_nop 0
	v_pk_add_f32 v[142:143], v[142:143], 1.0 op_sel_hi:[1,0]
	s_nop 0
	v_rcp_f32_e32 v91, v143
	s_nop 0
	s_nop 0
	v_mul_f32_e32 v146, v135, v91
	v_fma_f32 v147, -v143, v146, v135
	v_fma_f32 v87, v147, v91, v146
	v_rcp_f32_e32 v94, v142
	v_div_fixup_f32 v87, v87, v143, v135
	s_nop 0
	v_mul_f32_e32 v143, v134, v94
	v_fma_f32 v146, -v142, v143, v134
	v_fma_f32 v91, v146, v94, v143
	v_div_fixup_f32 v91, v91, v142, v134
	v_pk_fma_f32 v[134:135], v[140:141], v[102:103], v[138:139]
	v_cvt_pk_bf16_f32 v87, v91, v87
	v_pk_fma_f32 v[134:135], v[144:145], v[98:99], v[134:135]
	v_pk_fma_f32 v[102:103], v[136:137], v[102:103], 0 op_sel_hi:[1,1,0]
	v_pk_fma_f32 v[134:135], v[148:149], v[110:111], v[134:135]
	v_pk_fma_f32 v[98:99], v[140:141], v[98:99], v[102:103]
	v_pk_fma_f32 v[134:135], v[152:153], v[106:107], v[134:135]
	v_pk_fma_f32 v[98:99], v[144:145], v[110:111], v[98:99]
	v_mul_f32_e32 v91, 0xbfb8aa3b, v134
	v_exp_f32_e32 v138, v91
	v_mul_f32_e32 v91, 0xbfb8aa3b, v135
	v_exp_f32_e32 v139, v91
	v_pk_fma_f32 v[98:99], v[148:149], v[106:107], v[98:99]
	v_lshlrev_b32_e32 v140, 16, v84
	v_and_b32_e32 v141, 0xffff0000, v84
	v_pk_add_f32 v[138:139], v[138:139], 1.0 op_sel_hi:[1,0]
	v_lshlrev_b32_e32 v136, 16, v88
	v_rcp_f32_e32 v94, v139
	v_and_b32_e32 v137, 0xffff0000, v88
	v_pk_fma_f32 v[140:141], v[114:115], v[140:141], 0 op_sel_hi:[1,1,0]
	v_and_b32_e32 v111, 0xffff0000, v92
	s_nop 0
	v_mul_f32_e32 v143, v135, v94
	v_fma_f32 v146, -v139, v143, v135
	v_fma_f32 v91, v146, v94, v143
	v_div_fixup_f32 v91, v91, v139, v135
	v_rcp_f32_e32 v135, v138
	v_lshlrev_b32_e32 v144, 16, v54
	v_and_b32_e32 v145, 0xffff0000, v54
	s_nop 0
	v_mul_f32_e32 v142, v134, v135
	v_fma_f32 v143, -v138, v142, v134
	v_fma_f32 v94, v143, v135, v142
	v_div_fixup_f32 v94, v94, v138, v134
	v_cvt_pk_bf16_f32 v91, v94, v91
	v_lshlrev_b32_e32 v94, 16, v95
	v_and_b32_e32 v95, 0xffff0000, v95
	v_pk_fma_f32 v[94:95], v[152:153], v[94:95], v[98:99]
	v_pk_fma_f32 v[138:139], v[114:115], v[136:137], 0 op_sel_hi:[1,1,0]
	v_mul_f32_e32 v98, 0xbfb8aa3b, v94
	v_mul_f32_e32 v99, 0xbfb8aa3b, v95
	v_exp_f32_e32 v98, v98
	v_exp_f32_e32 v99, v99
	v_pk_fma_f32 v[136:137], v[118:119], v[136:137], v[140:141]
	v_lshlrev_b32_e32 v140, 16, v58
	v_and_b32_e32 v141, 0xffff0000, v58
	v_pk_add_f32 v[98:99], v[98:99], 1.0 op_sel_hi:[1,0]
	s_nop 0
	v_rcp_f32_e32 v103, v99
	s_nop 0
	s_nop 0
	v_mul_f32_e32 v107, v95, v103
	v_fma_f32 v110, -v99, v107, v95
	v_fma_f32 v102, v110, v103, v107
	v_div_fixup_f32 v142, v102, v99, v95
	v_rcp_f32_e32 v99, v98
	v_lshlrev_b32_e32 v110, 16, v92
	v_pk_fma_f32 v[134:135], v[114:115], v[110:111], 0 op_sel_hi:[1,1,0]
	v_pk_fma_f32 v[138:139], v[118:119], v[110:111], v[138:139]
	s_nop 0
	v_mul_f32_e32 v103, v94, v99
	v_fma_f32 v106, -v98, v103, v94
	v_fma_f32 v95, v106, v99, v103
	v_div_fixup_f32 v143, v95, v98, v94
	v_lshlrev_b32_e32 v94, 16, v104
	v_and_b32_e32 v95, 0xffff0000, v104
	v_pk_fma_f32 v[110:111], v[122:123], v[110:111], v[136:137]
	v_lshlrev_b32_e32 v98, 16, v100
	v_and_b32_e32 v99, 0xffff0000, v100
	v_pk_fma_f32 v[110:111], v[126:127], v[94:95], v[110:111]
	v_lshlrev_b32_e32 v106, 16, v108
	s_waitcnt vmcnt(0)
	v_pk_fma_f32 v[110:111], v[130:131], v[98:99], v[110:111]
	v_and_b32_e32 v107, 0xffff0000, v108
	v_mul_f32_e32 v84, 0xbfb8aa3b, v110
	v_exp_f32_e32 v136, v84
	v_mul_f32_e32 v84, 0xbfb8aa3b, v111
	v_exp_f32_e32 v137, v84
	v_lshlrev_b32_e32 v102, 16, v112
	v_and_b32_e32 v103, 0xffff0000, v112
	v_pk_add_f32 v[136:137], v[136:137], 1.0 op_sel_hi:[1,0]
	s_nop 0
	v_rcp_f32_e32 v88, v137
	s_nop 0
	s_nop 0
	v_mul_f32_e32 v100, v111, v88
	v_fma_f32 v104, -v137, v100, v111
	v_fma_f32 v84, v104, v88, v100
	v_rcp_f32_e32 v92, v136
	v_div_fixup_f32 v84, v84, v137, v111
	s_nop 0
	v_mul_f32_e32 v104, v110, v92
	v_fma_f32 v108, -v136, v104, v110
	v_fma_f32 v88, v108, v92, v104
	v_div_fixup_f32 v88, v88, v136, v110
	v_pk_fma_f32 v[110:111], v[122:123], v[94:95], v[138:139]
	v_cvt_pk_bf16_f32 v84, v88, v84
	v_pk_fma_f32 v[110:111], v[126:127], v[98:99], v[110:111]
	v_lshlrev_b32_e32 v138, 16, v62
	v_pk_fma_f32 v[110:111], v[130:131], v[102:103], v[110:111]
	v_and_b32_e32 v139, 0xffff0000, v62
	v_mul_f32_e32 v88, 0xbfb8aa3b, v110
	v_exp_f32_e32 v136, v88
	v_mul_f32_e32 v88, 0xbfb8aa3b, v111
	v_exp_f32_e32 v137, v88
	s_nop 0
	v_pk_add_f32 v[136:137], v[136:137], 1.0 op_sel_hi:[1,0]
	s_nop 0
	v_rcp_f32_e32 v92, v137
	s_nop 0
	s_nop 0
	v_mul_f32_e32 v104, v111, v92
	v_fma_f32 v108, -v137, v104, v111
	v_fma_f32 v88, v108, v92, v104
	v_rcp_f32_e32 v100, v136
	v_div_fixup_f32 v88, v88, v137, v111
	s_nop 0
	v_mul_f32_e32 v108, v110, v100
	v_fma_f32 v111, -v136, v108, v110
	v_fma_f32 v92, v111, v100, v108
	v_div_fixup_f32 v92, v92, v136, v110
	v_pk_fma_f32 v[110:111], v[118:119], v[94:95], v[134:135]
	v_cvt_pk_bf16_f32 v88, v92, v88
	v_pk_fma_f32 v[110:111], v[122:123], v[98:99], v[110:111]
	v_pk_fma_f32 v[94:95], v[114:115], v[94:95], 0 op_sel_hi:[1,1,0]
	v_pk_fma_f32 v[110:111], v[126:127], v[102:103], v[110:111]
	v_pk_fma_f32 v[94:95], v[118:119], v[98:99], v[94:95]
	v_pk_fma_f32 v[110:111], v[130:131], v[106:107], v[110:111]
	v_pk_fma_f32 v[94:95], v[122:123], v[102:103], v[94:95]
	v_mul_f32_e32 v92, 0xbfb8aa3b, v110
	v_exp_f32_e32 v134, v92
	v_mul_f32_e32 v92, 0xbfb8aa3b, v111
	v_exp_f32_e32 v135, v92
	v_pk_fma_f32 v[94:95], v[126:127], v[106:107], v[94:95]
	v_lshlrev_b32_e32 v98, 16, v96
	v_and_b32_e32 v99, 0xffff0000, v96
	v_pk_add_f32 v[134:135], v[134:135], 1.0 op_sel_hi:[1,0]
	v_pk_fma_f32 v[94:95], v[130:131], v[98:99], v[94:95]
	v_rcp_f32_e32 v100, v135
	v_mul_f32_e32 v96, 0xbfb8aa3b, v94
	v_exp_f32_e32 v98, v96
	v_mul_f32_e32 v96, 0xbfb8aa3b, v95
	s_nop 0
	v_mul_f32_e32 v108, v111, v100
	v_fma_f32 v112, -v135, v108, v111
	v_fma_f32 v92, v112, v100, v108
	v_rcp_f32_e32 v104, v134
	v_div_fixup_f32 v92, v92, v135, v111
	v_exp_f32_e32 v99, v96
	v_lshlrev_b32_e32 v122, 16, v70
	s_nop 0
	v_mul_f32_e32 v111, v110, v104
	v_fma_f32 v112, -v134, v111, v110
	v_fma_f32 v100, v112, v104, v111
	v_pk_add_f32 v[98:99], v[98:99], 1.0 op_sel_hi:[1,0]
	v_div_fixup_f32 v100, v100, v134, v110
	v_cvt_pk_bf16_f32 v92, v100, v92
	v_rcp_f32_e32 v100, v99
	v_lshlrev_b32_e32 v112, 16, v85
	v_lshlrev_b32_e32 v108, 16, v89
	v_and_b32_e32 v123, 0xffff0000, v70
	s_nop 0
	v_mul_f32_e32 v103, v95, v100
	v_fma_f32 v104, -v99, v103, v95
	v_fma_f32 v96, v104, v100, v103
	v_div_fixup_f32 v114, v96, v99, v95
	v_rcp_f32_e32 v96, v98
	v_and_b32_e32 v103, 0xffff0000, v109
	v_lshlrev_b32_e32 v104, 16, v93
	v_lshlrev_b32_e32 v126, 16, v78
	s_nop 0
	v_mul_f32_e32 v100, v94, v96
	v_fma_f32 v102, -v98, v100, v94
	v_fma_f32 v95, v102, v96, v100
	v_div_fixup_f32 v115, v95, v98, v94
	v_lshlrev_b32_e32 v98, 16, v101
	v_and_b32_e32 v99, 0xffff0000, v101
	v_lshlrev_b32_e32 v100, 16, v113
	v_and_b32_e32 v101, 0xffff0000, v113
	v_and_b32_e32 v113, 0xffff0000, v85
	v_lshlrev_b32_e32 v102, 16, v109
	v_and_b32_e32 v109, 0xffff0000, v89
	v_pk_fma_f32 v[112:113], v[116:117], v[112:113], 0 op_sel_hi:[1,1,0]
	v_lshlrev_b32_e32 v94, 16, v105
	v_and_b32_e32 v95, 0xffff0000, v105
	v_and_b32_e32 v105, 0xffff0000, v93
	v_pk_fma_f32 v[110:111], v[116:117], v[108:109], 0 op_sel_hi:[1,1,0]
	v_pk_fma_f32 v[108:109], v[120:121], v[108:109], v[112:113]
	v_pk_fma_f32 v[106:107], v[116:117], v[104:105], 0 op_sel_hi:[1,1,0]
	v_pk_fma_f32 v[110:111], v[120:121], v[104:105], v[110:111]
	v_pk_fma_f32 v[104:105], v[124:125], v[104:105], v[108:109]
	v_and_b32_e32 v127, 0xffff0000, v78
	v_pk_fma_f32 v[104:105], v[128:129], v[94:95], v[104:105]
	v_lshlrev_b32_e32 v134, 7, v170
	v_pk_fma_f32 v[104:105], v[132:133], v[98:99], v[104:105]
	s_nop 0
	v_mul_f32_e32 v85, 0xbfb8aa3b, v104
	v_exp_f32_e32 v108, v85
	v_mul_f32_e32 v85, 0xbfb8aa3b, v105
	v_exp_f32_e32 v109, v85
	s_nop 0
	v_pk_add_f32 v[108:109], v[108:109], 1.0 op_sel_hi:[1,0]
	s_nop 0
	v_rcp_f32_e32 v89, v109
	s_nop 0
	s_nop 0
	v_mul_f32_e32 v96, v105, v89
	v_fma_f32 v112, -v109, v96, v105
	v_fma_f32 v85, v112, v89, v96
	v_rcp_f32_e32 v93, v108
	v_div_fixup_f32 v85, v85, v109, v105
	s_nop 0
	v_mul_f32_e32 v105, v104, v93
	v_fma_f32 v109, -v108, v105, v104
	v_fma_f32 v89, v109, v93, v105
	v_div_fixup_f32 v89, v89, v108, v104
	v_pk_fma_f32 v[104:105], v[124:125], v[94:95], v[110:111]
	v_cvt_pk_bf16_f32 v85, v89, v85
	v_pk_fma_f32 v[104:105], v[128:129], v[98:99], v[104:105]
	s_nop 0
	v_pk_fma_f32 v[104:105], v[132:133], v[100:101], v[104:105]
	s_nop 0
	v_mul_f32_e32 v89, 0xbfb8aa3b, v104
	v_exp_f32_e32 v108, v89
	v_mul_f32_e32 v89, 0xbfb8aa3b, v105
	v_exp_f32_e32 v109, v89
	s_nop 0
	v_pk_add_f32 v[108:109], v[108:109], 1.0 op_sel_hi:[1,0]
	s_nop 0
	v_rcp_f32_e32 v93, v109
	s_nop 0
	s_nop 0
	v_mul_f32_e32 v110, v105, v93
	v_fma_f32 v111, -v109, v110, v105
	v_fma_f32 v89, v111, v93, v110
	v_rcp_f32_e32 v96, v108
	v_div_fixup_f32 v89, v89, v109, v105
	s_nop 0
	v_mul_f32_e32 v109, v104, v96
	v_fma_f32 v110, -v108, v109, v104
	v_fma_f32 v93, v110, v96, v109
	v_div_fixup_f32 v93, v93, v108, v104
	v_pk_fma_f32 v[104:105], v[120:121], v[94:95], v[106:107]
	v_cvt_pk_bf16_f32 v89, v93, v89
	v_pk_fma_f32 v[104:105], v[124:125], v[98:99], v[104:105]
	v_pk_fma_f32 v[94:95], v[116:117], v[94:95], 0 op_sel_hi:[1,1,0]
	v_pk_fma_f32 v[104:105], v[128:129], v[100:101], v[104:105]
	v_pk_fma_f32 v[94:95], v[120:121], v[98:99], v[94:95]
	v_pk_fma_f32 v[104:105], v[132:133], v[102:103], v[104:105]
	v_pk_fma_f32 v[94:95], v[124:125], v[100:101], v[94:95]
	v_mul_f32_e32 v93, 0xbfb8aa3b, v104
	v_exp_f32_e32 v106, v93
	v_mul_f32_e32 v93, 0xbfb8aa3b, v105
	v_exp_f32_e32 v107, v93
	v_pk_fma_f32 v[94:95], v[128:129], v[102:103], v[94:95]
	v_lshlrev_b32_e32 v124, 16, v66
	v_and_b32_e32 v125, 0xffff0000, v66
	v_pk_add_f32 v[106:107], v[106:107], 1.0 op_sel_hi:[1,0]
	v_lshlrev_b32_e32 v128, 16, v74
	v_rcp_f32_e32 v96, v107
	v_and_b32_e32 v129, 0xffff0000, v74
	s_nop 0
	v_mul_f32_e32 v109, v105, v96
	v_fma_f32 v110, -v107, v109, v105
	v_fma_f32 v93, v110, v96, v109
	v_div_fixup_f32 v93, v93, v107, v105
	v_rcp_f32_e32 v105, v106
	s_nop 0
	s_nop 0
	v_mul_f32_e32 v108, v104, v105
	v_fma_f32 v109, -v106, v108, v104
	v_fma_f32 v96, v109, v105, v108
	v_div_fixup_f32 v96, v96, v106, v104
	v_cvt_pk_bf16_f32 v93, v96, v93
	v_lshlrev_b32_e32 v96, 16, v97
	v_and_b32_e32 v97, 0xffff0000, v97
	v_pk_fma_f32 v[94:95], v[132:133], v[96:97], v[94:95]
	s_nop 0
	v_mul_f32_e32 v96, 0xbfb8aa3b, v94
	v_mul_f32_e32 v97, 0xbfb8aa3b, v95
	v_exp_f32_e32 v96, v96
	v_exp_f32_e32 v97, v97
	s_nop 0
	v_pk_add_f32 v[96:97], v[96:97], 1.0 op_sel_hi:[1,0]
	s_nop 0
	v_rcp_f32_e32 v99, v97
	s_nop 0
	s_nop 0
	v_mul_f32_e32 v101, v95, v99
	v_fma_f32 v102, -v97, v101, v95
	v_fma_f32 v98, v102, v99, v101
	v_div_fixup_f32 v97, v98, v97, v95
	v_rcp_f32_e32 v98, v96
	s_movk_i32 s0, 0xc0
	s_nop 0
	v_mul_f32_e32 v100, v94, v98
	v_fma_f32 v101, -v96, v100, v94
	v_fma_f32 v95, v101, v98, v100
	v_div_fixup_f32 v98, v95, v96, v94
	v_lshlrev_b32_e32 v99, 6, v170
	v_cvt_pk_bf16_f32 v97, v98, v97
	v_lshlrev_b32_e32 v98, 10, v170
	v_bitop3_b32 v99, v99, v178, s0 bitop3:0x6c
	v_add3_u32 v132, 0, v98, v99
	ds_write_b128 v132, v[82:85]
	v_or_b32_e32 v82, 1, v176
	v_lshlrev_b32_e32 v83, 8, v82
	v_lshlrev_b32_e32 v82, 4, v82
	s_movk_i32 s0, 0xd0
	v_bitop3_b32 v82, v82, v178, s0 bitop3:0x6c
	v_add3_u32 v133, 0, v83, v82
	v_or_b32_e32 v82, 2, v176
	v_lshlrev_b32_e32 v83, 8, v82
	v_lshlrev_b32_e32 v82, 4, v82
	s_movk_i32 s0, 0xe0
	v_bitop3_b32 v82, v82, v178, s0 bitop3:0x6c
	v_add3_u32 v135, 0, v83, v82
	v_or_b32_e32 v82, 3, v176
	v_lshlrev_b32_e32 v83, 8, v82
	v_lshlrev_b32_e32 v82, 4, v82
	s_movk_i32 s0, 0xf0
	v_bitop3_b32 v82, v82, v178, s0 bitop3:0x6c
	v_cvt_pk_bf16_f32 v94, v165, v155
	v_cvt_pk_bf16_f32 v95, v143, v142
	v_cvt_pk_bf16_f32 v96, v115, v114
	v_add3_u32 v136, 0, v83, v82
	ds_write_b128 v133, v[86:89]
	ds_write_b128 v135, v[90:93]
	ds_write_b128 v136, v[94:97]
	global_load_dwordx4 v[82:85], v164, s[34:35] offset:2064
	global_load_dwordx4 v[90:93], v164, s[34:35] offset:2048
	s_mov_b64 s[0:1], 0x1800
	v_lshl_add_u64 v[86:87], v[156:157], 0, s[0:1]
	s_mov_b64 s[0:1], 0x2800
	global_load_dwordx4 v[94:97], v[166:167], off offset:2048
	s_nop 0
	global_load_dwordx4 v[86:89], v[86:87], off offset:16
	v_lshl_add_u64 v[98:99], v[156:157], 0, s[0:1]
	s_mov_b64 s[0:1], 0x3800
	global_load_dwordx4 v[106:109], v[158:159], off offset:2048
	s_nop 0
	global_load_dwordx4 v[98:101], v[98:99], off offset:16
	v_lshl_add_u64 v[102:103], v[156:157], 0, s[0:1]
	s_mov_b64 s[0:1], 0x4800
	global_load_dwordx4 v[110:113], v[162:163], off offset:2048
	s_nop 0
	global_load_dwordx4 v[102:105], v[102:103], off offset:16
	v_lshl_add_u64 v[118:119], v[156:157], 0, s[0:1]
	global_load_dwordx4 v[114:117], v[160:161], off offset:2048
	s_nop 0
	global_load_dwordx4 v[118:121], v[118:119], off offset:16
	s_waitcnt vmcnt(8)
	v_pk_fma_f32 v[144:145], v[90:91], v[144:145], 0 op_sel_hi:[1,1,0]
	v_pk_fma_f32 v[142:143], v[90:91], v[140:141], 0 op_sel_hi:[1,1,0]
	v_pk_fma_f32 v[130:131], v[90:91], v[138:139], 0 op_sel_hi:[1,1,0]
	s_waitcnt vmcnt(7)
	v_pk_fma_f32 v[140:141], v[94:95], v[140:141], v[144:145]
	v_pk_fma_f32 v[142:143], v[94:95], v[138:139], v[142:143]
	v_pk_fma_f32 v[130:131], v[94:95], v[122:123], v[130:131]
	s_waitcnt vmcnt(5)
	v_pk_fma_f32 v[138:139], v[106:107], v[138:139], v[140:141]
	v_pk_fma_f32 v[130:131], v[106:107], v[124:125], v[130:131]
	v_pk_fma_f32 v[90:91], v[90:91], v[122:123], 0 op_sel_hi:[1,1,0]
	s_waitcnt vmcnt(3)
	v_pk_fma_f32 v[138:139], v[110:111], v[122:123], v[138:139]
	v_pk_fma_f32 v[130:131], v[110:111], v[126:127], v[130:131]
	s_waitcnt vmcnt(1)
	v_pk_fma_f32 v[138:139], v[114:115], v[124:125], v[138:139]
	v_pk_fma_f32 v[130:131], v[114:115], v[128:129], v[130:131]
	v_mul_f32_e32 v54, 0xbfb8aa3b, v138
	v_exp_f32_e32 v140, v54
	v_mul_f32_e32 v54, 0xbfb8aa3b, v139
	v_exp_f32_e32 v141, v54
	v_pk_fma_f32 v[90:91], v[94:95], v[124:125], v[90:91]
	v_lshlrev_b32_e32 v94, 16, v50
	v_pk_fma_f32 v[90:91], v[106:107], v[126:127], v[90:91]
	v_pk_add_f32 v[140:141], v[140:141], 1.0 op_sel_hi:[1,0]
	v_pk_fma_f32 v[90:91], v[110:111], v[128:129], v[90:91]
	v_rcp_f32_e32 v58, v141
	v_and_b32_e32 v95, 0xffff0000, v50
	v_pk_fma_f32 v[90:91], v[114:115], v[94:95], v[90:91]
	s_nop 0
	v_mul_f32_e32 v66, v139, v58
	v_fma_f32 v70, -v141, v66, v139
	v_fma_f32 v54, v70, v58, v66
	v_div_fixup_f32 v139, v54, v141, v139
	v_rcp_f32_e32 v58, v140
	v_mul_f32_e32 v50, 0xbfb8aa3b, v90
	v_exp_f32_e32 v94, v50
	v_mul_f32_e32 v50, 0xbfb8aa3b, v91
	s_nop 0
	v_mul_f32_e32 v66, v138, v58
	v_fma_f32 v70, -v140, v66, v138
	v_fma_f32 v54, v70, v58, v66
	v_div_fixup_f32 v138, v54, v140, v138
	v_pk_mul_f32 v[138:139], v[138:139], s[26:27] op_sel_hi:[1,0]
	v_exp_f32_e32 v95, v50
	v_cvt_pk_bf16_f32 v54, v138, v139
	v_pk_fma_f32 v[138:139], v[106:107], v[122:123], v[142:143]
	v_lshlrev_b32_e32 v122, 16, v55
	v_pk_fma_f32 v[138:139], v[110:111], v[124:125], v[138:139]
	v_pk_add_f32 v[94:95], v[94:95], 1.0 op_sel_hi:[1,0]
	v_pk_fma_f32 v[138:139], v[114:115], v[126:127], v[138:139]
	v_mul_f32_e32 v58, 0xbfb8aa3b, v138
	v_exp_f32_e32 v140, v58
	v_mul_f32_e32 v58, 0xbfb8aa3b, v139
	v_exp_f32_e32 v141, v58
	v_and_b32_e32 v123, 0xffff0000, v55
	v_lshlrev_b32_e32 v110, 16, v59
	v_and_b32_e32 v111, 0xffff0000, v59
	v_pk_add_f32 v[140:141], v[140:141], 1.0 op_sel_hi:[1,0]
	v_pk_fma_f32 v[122:123], v[92:93], v[122:123], 0 op_sel_hi:[1,1,0]
	v_rcp_f32_e32 v62, v141
	v_lshlrev_b32_e32 v106, 16, v63
	v_and_b32_e32 v107, 0xffff0000, v63
	v_pk_fma_f32 v[114:115], v[92:93], v[110:111], 0 op_sel_hi:[1,1,0]
	s_nop 0
	v_mul_f32_e32 v70, v139, v62
	v_fma_f32 v74, -v141, v70, v139
	v_fma_f32 v58, v74, v62, v70
	v_div_fixup_f32 v139, v58, v141, v139
	v_rcp_f32_e32 v62, v140
	v_pk_fma_f32 v[110:111], v[96:97], v[110:111], v[122:123]
	v_pk_fma_f32 v[114:115], v[96:97], v[106:107], v[114:115]
	s_nop 0
	v_mul_f32_e32 v70, v138, v62
	v_fma_f32 v74, -v140, v70, v138
	v_fma_f32 v58, v74, v62, v70
	v_div_fixup_f32 v138, v58, v140, v138
	v_pk_mul_f32 v[138:139], v[138:139], s[26:27] op_sel_hi:[1,0]
	v_mul_f32_e32 v62, 0xbfb8aa3b, v130
	v_cvt_pk_bf16_f32 v58, v138, v139
	v_exp_f32_e32 v138, v62
	v_mul_f32_e32 v62, 0xbfb8aa3b, v131
	v_exp_f32_e32 v139, v62
	s_nop 0
	v_pk_add_f32 v[138:139], v[138:139], 1.0 op_sel_hi:[1,0]
	s_nop 0
	v_rcp_f32_e32 v66, v139
	s_nop 0
	s_nop 0
	v_mul_f32_e32 v74, v131, v66
	v_fma_f32 v78, -v139, v74, v131
	v_fma_f32 v62, v78, v66, v74
	v_div_fixup_f32 v131, v62, v139, v131
	v_rcp_f32_e32 v66, v138
	s_nop 0
	s_nop 0
	v_mul_f32_e32 v74, v130, v66
	v_fma_f32 v78, -v138, v74, v130
	v_fma_f32 v62, v78, v66, v74
	v_rcp_f32_e32 v66, v95
	v_div_fixup_f32 v130, v62, v138, v130
	v_pk_mul_f32 v[130:131], v[130:131], s[26:27] op_sel_hi:[1,0]
	s_nop 0
	v_mul_f32_e32 v74, v91, v66
	v_fma_f32 v78, -v95, v74, v91
	v_fma_f32 v50, v78, v66, v74
	v_div_fixup_f32 v91, v50, v95, v91
	v_rcp_f32_e32 v66, v94
	v_cvt_pk_bf16_f32 v62, v130, v131
	s_nop 0
	v_mul_f32_e32 v74, v90, v66
	v_fma_f32 v78, -v94, v74, v90
	v_fma_f32 v50, v78, v66, v74
	v_div_fixup_f32 v90, v50, v94, v90
	v_lshlrev_b32_e32 v70, 16, v71
	v_and_b32_e32 v71, 0xffff0000, v71
	v_pk_fma_f32 v[94:95], v[92:93], v[106:107], 0 op_sel_hi:[1,1,0]
	v_pk_fma_f32 v[106:107], v[108:109], v[106:107], v[110:111]
	v_lshlrev_b32_e32 v66, 16, v67
	v_and_b32_e32 v67, 0xffff0000, v67
	v_pk_fma_f32 v[106:107], v[112:113], v[70:71], v[106:107]
	v_lshlrev_b32_e32 v78, 16, v79
	v_pk_fma_f32 v[106:107], v[116:117], v[66:67], v[106:107]
	v_and_b32_e32 v79, 0xffff0000, v79
	v_mul_f32_e32 v50, 0xbfb8aa3b, v106
	v_exp_f32_e32 v110, v50
	v_mul_f32_e32 v50, 0xbfb8aa3b, v107
	v_exp_f32_e32 v111, v50
	v_pk_fma_f32 v[94:95], v[96:97], v[70:71], v[94:95]
	v_lshlrev_b32_e32 v74, 16, v75
	v_pk_fma_f32 v[94:95], v[108:109], v[66:67], v[94:95]
	v_pk_add_f32 v[110:111], v[110:111], 1.0 op_sel_hi:[1,0]
	v_and_b32_e32 v75, 0xffff0000, v75
	v_rcp_f32_e32 v55, v111
	v_pk_fma_f32 v[94:95], v[112:113], v[78:79], v[94:95]
	v_pk_mul_f32 v[90:91], v[90:91], s[26:27] op_sel_hi:[1,0]
	v_pk_fma_f32 v[94:95], v[116:117], v[74:75], v[94:95]
	s_nop 0
	v_mul_f32_e32 v63, v107, v55
	v_fma_f32 v122, -v111, v63, v107
	v_fma_f32 v50, v122, v55, v63
	v_div_fixup_f32 v107, v50, v111, v107
	v_rcp_f32_e32 v55, v110
	s_nop 0
	s_nop 0
	v_mul_f32_e32 v63, v106, v55
	v_fma_f32 v111, -v110, v63, v106
	v_fma_f32 v50, v111, v55, v63
	v_div_fixup_f32 v106, v50, v110, v106
	v_pk_mul_f32 v[106:107], v[106:107], s[26:27] op_sel_hi:[1,0]
	s_nop 0
	v_cvt_pk_bf16_f32 v55, v106, v107
	v_pk_fma_f32 v[106:107], v[108:109], v[70:71], v[114:115]
	v_pk_fma_f32 v[70:71], v[92:93], v[70:71], 0 op_sel_hi:[1,1,0]
	v_pk_fma_f32 v[106:107], v[112:113], v[66:67], v[106:107]
	v_pk_fma_f32 v[66:67], v[96:97], v[66:67], v[70:71]
	v_pk_fma_f32 v[106:107], v[116:117], v[78:79], v[106:107]
	v_pk_fma_f32 v[66:67], v[108:109], v[78:79], v[66:67]
	v_mul_f32_e32 v50, 0xbfb8aa3b, v106
	v_exp_f32_e32 v110, v50
	v_mul_f32_e32 v50, 0xbfb8aa3b, v107
	v_exp_f32_e32 v111, v50
	v_pk_fma_f32 v[66:67], v[112:113], v[74:75], v[66:67]
	v_lshlrev_b32_e32 v108, 16, v56
	v_and_b32_e32 v109, 0xffff0000, v56
	v_pk_add_f32 v[110:111], v[110:111], 1.0 op_sel_hi:[1,0]
	v_lshlrev_b32_e32 v96, 16, v60
	v_rcp_f32_e32 v59, v111
	v_and_b32_e32 v97, 0xffff0000, v60
	v_pk_fma_f32 v[108:109], v[82:83], v[108:109], 0 op_sel_hi:[1,1,0]
	v_and_b32_e32 v79, 0xffff0000, v76
	s_nop 0
	v_mul_f32_e32 v114, v107, v59
	v_fma_f32 v115, -v111, v114, v107
	v_fma_f32 v50, v115, v59, v114
	v_div_fixup_f32 v107, v50, v111, v107
	v_rcp_f32_e32 v59, v110
	s_nop 0
	s_nop 0
	v_mul_f32_e32 v111, v106, v59
	v_fma_f32 v114, -v110, v111, v106
	v_fma_f32 v50, v114, v59, v111
	v_div_fixup_f32 v106, v50, v110, v106
	v_pk_mul_f32 v[106:107], v[106:107], s[26:27] op_sel_hi:[1,0]
	v_mul_f32_e32 v50, 0xbfb8aa3b, v94
	v_cvt_pk_bf16_f32 v59, v106, v107
	v_exp_f32_e32 v106, v50
	v_mul_f32_e32 v50, 0xbfb8aa3b, v95
	v_exp_f32_e32 v107, v50
	s_nop 0
	v_pk_add_f32 v[106:107], v[106:107], 1.0 op_sel_hi:[1,0]
	s_nop 0
	v_rcp_f32_e32 v63, v107
	s_nop 0
	s_nop 0
	v_mul_f32_e32 v111, v95, v63
	v_fma_f32 v114, -v107, v111, v95
	v_fma_f32 v50, v114, v63, v111
	v_div_fixup_f32 v95, v50, v107, v95
	v_rcp_f32_e32 v63, v106
	s_nop 0
	s_nop 0
	v_mul_f32_e32 v110, v94, v63
	v_fma_f32 v111, -v106, v110, v94
	v_fma_f32 v50, v111, v63, v110
	v_div_fixup_f32 v94, v50, v106, v94
	v_lshlrev_b32_e32 v50, 16, v51
	v_and_b32_e32 v51, 0xffff0000, v51
	v_pk_fma_f32 v[50:51], v[116:117], v[50:51], v[66:67]
	v_pk_mul_f32 v[94:95], v[94:95], s[26:27] op_sel_hi:[1,0]
	v_mul_f32_e32 v66, 0xbfb8aa3b, v50
	v_mul_f32_e32 v67, 0xbfb8aa3b, v51
	v_exp_f32_e32 v66, v66
	v_exp_f32_e32 v67, v67
	v_cvt_pk_bf16_f32 v63, v94, v95
	v_lshlrev_b32_e32 v94, 16, v64
	v_and_b32_e32 v95, 0xffff0000, v64
	v_pk_add_f32 v[66:67], v[66:67], 1.0 op_sel_hi:[1,0]
	v_pk_fma_f32 v[106:107], v[82:83], v[96:97], 0 op_sel_hi:[1,1,0]
	v_rcp_f32_e32 v71, v67
	v_pk_fma_f32 v[96:97], v[86:87], v[96:97], v[108:109]
	v_pk_fma_f32 v[92:93], v[82:83], v[94:95], 0 op_sel_hi:[1,1,0]
	v_pk_fma_f32 v[106:107], v[86:87], v[94:95], v[106:107]
	s_nop 0
	v_mul_f32_e32 v75, v51, v71
	v_fma_f32 v78, -v67, v75, v51
	v_fma_f32 v70, v78, v71, v75
	v_div_fixup_f32 v51, v70, v67, v51
	v_rcp_f32_e32 v70, v66
	v_pk_fma_f32 v[94:95], v[98:99], v[94:95], v[96:97]
	v_lshlrev_b32_e32 v78, 16, v76
	s_nop 0
	v_mul_f32_e32 v74, v50, v70
	v_fma_f32 v75, -v66, v74, v50
	v_fma_f32 v67, v75, v70, v74
	v_div_fixup_f32 v50, v67, v66, v50
	v_lshlrev_b32_e32 v66, 16, v72
	v_and_b32_e32 v67, 0xffff0000, v72
	v_lshlrev_b32_e32 v70, 16, v68
	v_and_b32_e32 v71, 0xffff0000, v68
	v_pk_fma_f32 v[94:95], v[102:103], v[66:67], v[94:95]
	v_lshlrev_b32_e32 v74, 16, v80
	s_waitcnt vmcnt(0)
	v_pk_fma_f32 v[94:95], v[118:119], v[70:71], v[94:95]
	v_and_b32_e32 v75, 0xffff0000, v80
	v_mul_f32_e32 v56, 0xbfb8aa3b, v94
	v_exp_f32_e32 v96, v56
	v_mul_f32_e32 v56, 0xbfb8aa3b, v95
	v_exp_f32_e32 v97, v56
	v_pk_fma_f32 v[92:93], v[86:87], v[66:67], v[92:93]
	v_pk_mul_f32 v[50:51], v[50:51], s[26:27] op_sel_hi:[1,0]
	v_pk_fma_f32 v[92:93], v[98:99], v[70:71], v[92:93]
	v_pk_add_f32 v[96:97], v[96:97], 1.0 op_sel_hi:[1,0]
	v_pk_fma_f32 v[92:93], v[102:103], v[74:75], v[92:93]
	v_rcp_f32_e32 v60, v97
	v_pk_fma_f32 v[92:93], v[118:119], v[78:79], v[92:93]
	s_nop 0
	v_mul_f32_e32 v68, v95, v60
	v_fma_f32 v72, -v97, v68, v95
	v_fma_f32 v56, v72, v60, v68
	v_div_fixup_f32 v95, v56, v97, v95
	v_rcp_f32_e32 v60, v96
	s_nop 0
	s_nop 0
	v_mul_f32_e32 v68, v94, v60
	v_fma_f32 v72, -v96, v68, v94
	v_fma_f32 v56, v72, v60, v68
	v_div_fixup_f32 v94, v56, v96, v94
	v_pk_mul_f32 v[94:95], v[94:95], s[26:27] op_sel_hi:[1,0]
	s_nop 0
	v_cvt_pk_bf16_f32 v56, v94, v95
	v_pk_fma_f32 v[94:95], v[98:99], v[66:67], v[106:107]
	v_pk_fma_f32 v[66:67], v[82:83], v[66:67], 0 op_sel_hi:[1,1,0]
	v_pk_fma_f32 v[94:95], v[102:103], v[70:71], v[94:95]
	v_pk_fma_f32 v[66:67], v[86:87], v[70:71], v[66:67]
	v_pk_fma_f32 v[94:95], v[118:119], v[74:75], v[94:95]
	v_pk_fma_f32 v[66:67], v[98:99], v[74:75], v[66:67]
	v_mul_f32_e32 v60, 0xbfb8aa3b, v94
	v_exp_f32_e32 v96, v60
	v_mul_f32_e32 v60, 0xbfb8aa3b, v95
	v_exp_f32_e32 v97, v60
	v_pk_fma_f32 v[66:67], v[102:103], v[78:79], v[66:67]
	v_lshlrev_b32_e32 v70, 16, v52
	v_and_b32_e32 v71, 0xffff0000, v52
	v_pk_add_f32 v[96:97], v[96:97], 1.0 op_sel_hi:[1,0]
	v_pk_fma_f32 v[66:67], v[118:119], v[70:71], v[66:67]
	v_rcp_f32_e32 v64, v97
	v_mul_f32_e32 v52, 0xbfb8aa3b, v66
	v_exp_f32_e32 v70, v52
	v_mul_f32_e32 v52, 0xbfb8aa3b, v67
	s_nop 0
	v_mul_f32_e32 v72, v95, v64
	v_fma_f32 v76, -v97, v72, v95
	v_fma_f32 v60, v76, v64, v72
	v_div_fixup_f32 v95, v60, v97, v95
	v_rcp_f32_e32 v64, v96
	v_exp_f32_e32 v71, v52
	v_lshlrev_b32_e32 v86, 16, v57
	v_and_b32_e32 v87, 0xffff0000, v57
	s_nop 0
	v_mul_f32_e32 v72, v94, v64
	v_fma_f32 v76, -v96, v72, v94
	v_fma_f32 v60, v76, v64, v72
	v_div_fixup_f32 v94, v60, v96, v94
	v_pk_mul_f32 v[94:95], v[94:95], s[26:27] op_sel_hi:[1,0]
	v_mul_f32_e32 v64, 0xbfb8aa3b, v92
	v_cvt_pk_bf16_f32 v60, v94, v95
	v_exp_f32_e32 v94, v64
	v_mul_f32_e32 v64, 0xbfb8aa3b, v93
	v_exp_f32_e32 v95, v64
	v_pk_add_f32 v[70:71], v[70:71], 1.0 op_sel_hi:[1,0]
	v_pk_fma_f32 v[86:87], v[84:85], v[86:87], 0 op_sel_hi:[1,1,0]
	v_pk_add_f32 v[94:95], v[94:95], 1.0 op_sel_hi:[1,0]
	v_lshlrev_b32_e32 v78, 16, v65
	v_rcp_f32_e32 v68, v95
	v_and_b32_e32 v79, 0xffff0000, v65
	s_nop 0
	v_mul_f32_e32 v76, v93, v68
	v_fma_f32 v80, -v95, v76, v93
	v_fma_f32 v64, v80, v68, v76
	v_div_fixup_f32 v93, v64, v95, v93
	v_rcp_f32_e32 v68, v94
	s_nop 0
	s_nop 0
	v_mul_f32_e32 v76, v92, v68
	v_fma_f32 v80, -v94, v76, v92
	v_fma_f32 v64, v80, v68, v76
	v_rcp_f32_e32 v68, v71
	v_lshlrev_b32_e32 v80, 16, v61
	v_div_fixup_f32 v92, v64, v94, v92
	v_pk_mul_f32 v[92:93], v[92:93], s[26:27] op_sel_hi:[1,0]
	s_nop 0
	v_mul_f32_e32 v74, v67, v68
	v_fma_f32 v75, -v71, v74, v67
	v_fma_f32 v52, v75, v68, v74
	v_div_fixup_f32 v67, v52, v71, v67
	v_rcp_f32_e32 v68, v70
	v_and_b32_e32 v75, 0xffff0000, v77
	v_cvt_pk_bf16_f32 v64, v92, v93
	s_nop 0
	v_mul_f32_e32 v72, v66, v68
	v_fma_f32 v74, -v70, v72, v66
	v_fma_f32 v52, v74, v68, v72
	v_div_fixup_f32 v66, v52, v70, v66
	v_lshlrev_b32_e32 v70, 16, v73
	v_and_b32_e32 v71, 0xffff0000, v73
	v_lshlrev_b32_e32 v72, 16, v81
	v_and_b32_e32 v73, 0xffff0000, v81
	v_and_b32_e32 v81, 0xffff0000, v61
	v_pk_fma_f32 v[82:83], v[84:85], v[80:81], 0 op_sel_hi:[1,1,0]
	v_pk_fma_f32 v[80:81], v[88:89], v[80:81], v[86:87]
	v_lshlrev_b32_e32 v74, 16, v77
	v_pk_fma_f32 v[76:77], v[84:85], v[78:79], 0 op_sel_hi:[1,1,0]
	v_pk_fma_f32 v[82:83], v[88:89], v[78:79], v[82:83]
	v_pk_fma_f32 v[78:79], v[100:101], v[78:79], v[80:81]
	v_lshlrev_b32_e32 v68, 16, v69
	v_and_b32_e32 v69, 0xffff0000, v69
	v_pk_fma_f32 v[78:79], v[104:105], v[70:71], v[78:79]
	v_pk_fma_f32 v[76:77], v[88:89], v[70:71], v[76:77]
	v_pk_fma_f32 v[78:79], v[120:121], v[68:69], v[78:79]
	v_pk_fma_f32 v[76:77], v[100:101], v[68:69], v[76:77]
	v_mul_f32_e32 v52, 0xbfb8aa3b, v78
	v_exp_f32_e32 v80, v52
	v_mul_f32_e32 v52, 0xbfb8aa3b, v79
	v_exp_f32_e32 v81, v52
	v_pk_fma_f32 v[76:77], v[104:105], v[72:73], v[76:77]
	v_pk_mul_f32 v[66:67], v[66:67], s[26:27] op_sel_hi:[1,0]
	v_pk_fma_f32 v[76:77], v[120:121], v[74:75], v[76:77]
	v_pk_add_f32 v[80:81], v[80:81], 1.0 op_sel_hi:[1,0]
	s_nop 0
	v_rcp_f32_e32 v57, v81
	s_nop 0
	s_nop 0
	v_mul_f32_e32 v65, v79, v57
	v_fma_f32 v86, -v81, v65, v79
	v_fma_f32 v52, v86, v57, v65
	v_div_fixup_f32 v79, v52, v81, v79
	v_rcp_f32_e32 v57, v80
	s_nop 0
	s_nop 0
	v_mul_f32_e32 v65, v78, v57
	v_fma_f32 v81, -v80, v65, v78
	v_fma_f32 v52, v81, v57, v65
	v_div_fixup_f32 v78, v52, v80, v78
	v_pk_mul_f32 v[78:79], v[78:79], s[26:27] op_sel_hi:[1,0]
	s_nop 0
	v_cvt_pk_bf16_f32 v57, v78, v79
	v_pk_fma_f32 v[78:79], v[100:101], v[70:71], v[82:83]
	v_pk_fma_f32 v[70:71], v[84:85], v[70:71], 0 op_sel_hi:[1,1,0]
	v_pk_fma_f32 v[78:79], v[104:105], v[68:69], v[78:79]
	v_pk_fma_f32 v[68:69], v[88:89], v[68:69], v[70:71]
	v_pk_fma_f32 v[78:79], v[120:121], v[72:73], v[78:79]
	v_pk_fma_f32 v[68:69], v[100:101], v[72:73], v[68:69]
	v_mul_f32_e32 v52, 0xbfb8aa3b, v78
	v_exp_f32_e32 v80, v52
	v_mul_f32_e32 v52, 0xbfb8aa3b, v79
	v_exp_f32_e32 v81, v52
	v_pk_fma_f32 v[68:69], v[104:105], v[74:75], v[68:69]
	ds_write_b128 v132, v[54:57] offset:32768
	v_pk_add_f32 v[80:81], v[80:81], 1.0 op_sel_hi:[1,0]
	s_nop 0
	v_rcp_f32_e32 v61, v81
	s_nop 0
	s_nop 0
	v_mul_f32_e32 v82, v79, v61
	v_fma_f32 v83, -v81, v82, v79
	v_fma_f32 v52, v83, v61, v82
	v_div_fixup_f32 v79, v52, v81, v79
	v_rcp_f32_e32 v61, v80
	s_nop 0
	s_nop 0
	v_mul_f32_e32 v81, v78, v61
	v_fma_f32 v82, -v80, v81, v78
	v_fma_f32 v52, v82, v61, v81
	v_div_fixup_f32 v78, v52, v80, v78
	v_pk_mul_f32 v[78:79], v[78:79], s[26:27] op_sel_hi:[1,0]
	v_mul_f32_e32 v52, 0xbfb8aa3b, v76
	v_cvt_pk_bf16_f32 v61, v78, v79
	v_exp_f32_e32 v78, v52
	v_mul_f32_e32 v52, 0xbfb8aa3b, v77
	v_exp_f32_e32 v79, v52
	s_nop 0
	v_pk_add_f32 v[78:79], v[78:79], 1.0 op_sel_hi:[1,0]
	s_nop 0
	v_rcp_f32_e32 v65, v79
	s_nop 0
	s_nop 0
	v_mul_f32_e32 v81, v77, v65
	v_fma_f32 v82, -v79, v81, v77
	v_fma_f32 v52, v82, v65, v81
	v_div_fixup_f32 v77, v52, v79, v77
	v_rcp_f32_e32 v65, v78
	s_nop 0
	s_nop 0
	v_mul_f32_e32 v80, v76, v65
	v_fma_f32 v81, -v78, v80, v76
	v_fma_f32 v52, v81, v65, v80
	v_div_fixup_f32 v76, v52, v78, v76
	v_lshlrev_b32_e32 v52, 16, v53
	v_and_b32_e32 v53, 0xffff0000, v53
	v_pk_fma_f32 v[52:53], v[120:121], v[52:53], v[68:69]
	v_pk_mul_f32 v[76:77], v[76:77], s[26:27] op_sel_hi:[1,0]
	v_mul_f32_e32 v68, 0xbfb8aa3b, v52
	v_mul_f32_e32 v69, 0xbfb8aa3b, v53
	v_exp_f32_e32 v68, v68
	v_exp_f32_e32 v69, v69
	v_cvt_pk_bf16_f32 v65, v76, v77
	v_pk_add_f32 v[68:69], v[68:69], 1.0 op_sel_hi:[1,0]
	s_nop 0
	v_rcp_f32_e32 v71, v69
	s_nop 0
	s_nop 0
	v_mul_f32_e32 v73, v53, v71
	v_fma_f32 v74, -v69, v73, v53
	v_fma_f32 v70, v74, v71, v73
	v_div_fixup_f32 v53, v70, v69, v53
	v_rcp_f32_e32 v70, v68
	s_mov_b64 s[0:1], -1
	s_nop 0
	v_mul_f32_e32 v72, v52, v70
	v_fma_f32 v73, -v68, v72, v52
	v_fma_f32 v69, v73, v70, v72
	v_div_fixup_f32 v52, v69, v68, v52
	v_pk_mul_f32 v[52:53], v[52:53], s[26:27] op_sel_hi:[1,0]
	v_cvt_pk_bf16_f32 v69, v50, v51
	v_lshlrev_b32_e32 v50, 6, v168
	v_cvt_pk_bf16_f32 v71, v52, v53
	v_and_b32_e32 v52, 0xffffc000, v50
	v_and_b32_e32 v50, 48, v176
	v_lshlrev_b32_e32 v51, 3, v170
	v_and_or_b32 v50, v51, 8, v50
	v_lshrrev_b32_e32 v51, 1, v50
	v_lshrrev_b32_e32 v50, 5, v169
	v_or_b32_e32 v51, v51, v50
	v_lshlrev_b32_e32 v53, 9, v51
	v_and_b32_e32 v51, 48, v178
	v_add3_u32 v52, s92, v52, v53
	v_and_b32_e32 v53, 0x100, v134
	v_add3_u32 v52, v52, v51, v53
	s_and_b64 vcc, exec, s[12:13]
	v_cvt_pk_bf16_f32 v68, v90, v91
	v_cvt_pk_bf16_f32 v70, v66, v67
	ds_write_b128 v52, v[34:37]
	ds_write_b128 v133, v[58:61] offset:32768
	ds_write_b128 v52, v[38:41] offset:64
	ds_write_b128 v135, v[62:65] offset:32768
	ds_write_b128 v52, v[42:45] offset:128
	ds_write_b128 v136, v[68:71] offset:32768
	ds_write_b128 v52, v[46:49] offset:192
	s_cbranch_vccz .LBB0_662
	s_cmp_lg_u32 s61, 1
	s_cbranch_scc1 .LBB0_661
	s_ashr_i32 s39, s38, 31
	s_lshl_b64 s[0:1], s[38:39], 9
	s_add_u32 s0, s16, s0
	v_lshlrev_b32_e32 v34, 2, v171
	s_addc_u32 s1, s17, s1
	v_add_u32_e32 v34, s94, v34
	s_waitcnt vmcnt(0)
	ds_write2st64_b32 v34, v226, v227 offset0:6 offset1:7

.LBB0_1393:
	s_endpgm
	s_nop 0
	s_nop 0
	s_nop 0
	s_nop 0
	s_nop 0
	s_nop 0
	s_nop 0
	s_nop 0
	s_nop 0
	s_nop 0
	s_nop 0
	s_nop 0
	s_nop 0
	s_nop 0
	s_nop 0
	s_nop 0
	s_nop 0
	s_nop 0
	s_nop 0
	s_nop 0
	s_nop 0
	s_nop 0
	s_nop 0
	s_nop 0
	s_nop 0
	s_nop 0
	s_nop 0
	s_nop 0
	s_nop 0
	s_nop 0
	s_nop 0
	s_nop 0
	s_nop 0
	s_nop 0
	s_nop 0
	s_nop 0
	s_nop 0
	s_nop 0
	s_nop 0
	s_nop 0
	s_nop 0
	s_nop 0
	s_nop 0
	s_nop 0
	s_nop 0
	s_nop 0
	s_nop 0
	s_nop 0
	s_nop 0
	s_nop 0
	s_nop 0
	s_nop 0
	s_nop 0
	s_nop 0
	s_nop 0
	s_nop 0
	s_nop 0
	s_nop 0
	s_nop 0
	s_nop 0
	s_nop 0
	s_nop 0
	s_nop 0
	s_nop 0
	s_nop 0
	s_nop 0
	s_nop 0
	s_nop 0
	s_nop 0
	s_nop 0
	s_nop 0
	s_nop 0
	s_nop 0
	s_nop 0
	s_nop 0
	s_nop 0
	s_nop 0
	s_nop 0
	s_nop 0
	s_nop 0
	s_nop 0
	s_nop 0
	s_nop 0
	s_nop 0
	s_nop 0
	s_nop 0
	s_nop 0
	s_nop 0
	s_nop 0
	s_nop 0
	s_nop 0
	s_nop 0
	s_nop 0
	s_nop 0
	s_nop 0
	s_nop 0
	s_nop 0
	s_nop 0
	s_nop 0
	s_nop 0
	s_nop 0
	s_nop 0
	s_nop 0
	s_nop 0
	s_nop 0
	s_nop 0
	s_nop 0
	s_nop 0
	s_nop 0
	s_nop 0
	s_nop 0
	s_nop 0
	s_nop 0
	s_nop 0
	s_nop 0
	s_nop 0
	s_nop 0
	s_nop 0
	s_nop 0
	s_nop 0
	s_nop 0
	s_nop 0
	s_nop 0
	s_nop 0
	s_nop 0
	s_nop 0
	s_nop 0
	s_nop 0
	s_nop 0
	s_nop 0
	s_nop 0
	s_nop 0
	s_nop 0
	s_nop 0
	s_nop 0
	s_nop 0
	s_nop 0
	s_nop 0
	s_nop 0
	s_nop 0
	s_nop 0
	s_nop 0
	s_nop 0
	s_nop 0
	s_nop 0
	s_nop 0
	s_nop 0
	s_nop 0
	s_nop 0
	s_nop 0
	s_nop 0
	s_nop 0
	s_nop 0
	s_nop 0
	s_nop 0
	s_nop 0
	s_nop 0
	s_nop 0
	s_nop 0
	s_nop 0
	s_nop 0
	s_nop 0
	s_nop 0
	s_nop 0
	s_nop 0
	s_nop 0
	s_nop 0
	s_nop 0
	s_nop 0
	s_nop 0
	s_nop 0
	s_nop 0
	s_nop 0
	s_nop 0
	s_nop 0
	s_nop 0
	s_nop 0
	s_nop 0
	s_nop 0
	s_nop 0
	s_nop 0
	s_nop 0
	s_nop 0
	s_nop 0
	s_nop 0
	s_nop 0
	s_nop 0
	s_nop 0
	s_nop 0
	s_nop 0
	s_nop 0
	s_nop 0
	s_nop 0
	s_nop 0
	s_nop 0
	s_nop 0
	s_nop 0
	s_nop 0
	s_nop 0
	s_nop 0
	s_nop 0
	s_nop 0
	s_nop 0
	s_nop 0
	s_nop 0
	s_nop 0
	s_nop 0
	s_nop 0
	s_nop 0
	s_nop 0
	s_nop 0
	s_nop 0
	s_nop 0
	s_nop 0
	s_nop 0
	s_nop 0
	s_nop 0
	s_nop 0
	s_nop 0
	s_nop 0
	s_nop 0
	s_nop 0
	s_nop 0
	s_nop 0
	s_nop 0
	s_nop 0
	s_nop 0
	s_nop 0
	s_nop 0
	s_nop 0
	s_nop 0
	s_nop 0
	s_nop 0
	s_nop 0
	s_nop 0
	s_nop 0
	s_nop 0
	s_nop 0
	s_nop 0
	s_nop 0
	s_nop 0
	s_nop 0
	s_nop 0
	s_nop 0
	s_nop 0
	s_nop 0
	s_nop 0
	s_nop 0
	s_nop 0
	s_nop 0
	s_nop 0
	s_nop 0
	s_nop 0
	s_nop 0
	s_nop 0
	s_nop 0
	s_nop 0
	s_nop 0
	s_nop 0
	s_nop 0
	s_nop 0
	s_nop 0
	s_nop 0
	s_nop 0
	s_nop 0
	s_nop 0
	s_nop 0
	s_nop 0
	s_nop 0
	s_nop 0
	s_nop 0
	s_endpgm
